# v8_zeroloop
# speedup vs baseline: 1.0203x; 1.0203x over previous
.LBB0_546:
	v_lshl_add_u32 v187, s16, 14, v180
	s_waitcnt lgkmcnt(3)
	v_mfma_f32_32x32x16_bf16 v[80:95], v[80:83], v[140:143], 0
	ds_read_b128 v[190:193], v185 offset:12416
	v_sub_f32_e32 v64, v64, v188
	v_exp_f32_e32 v198, v64
	v_sub_f32_e32 v64, v65, v188
	v_exp_f32_e32 v199, v64
	s_waitcnt lgkmcnt(3)
	v_mfma_f32_32x32x16_bf16 v[80:95], v[152:155], v[136:139], v[80:95]
	ds_read_b128 v[194:197], v184 offset:12416
	v_sub_f32_e32 v64, v66, v188
	v_exp_f32_e32 v200, v64
	v_sub_f32_e32 v64, v67, v188
	v_exp_f32_e32 v201, v64
	s_waitcnt lgkmcnt(3)
	v_mfma_f32_32x32x16_bf16 v[80:95], v[148:151], v[132:135], v[80:95]
	ds_read_b128 v[64:67], v183 offset:12416
	v_sub_f32_e32 v68, v68, v188
	v_exp_f32_e32 v202, v68
	v_sub_f32_e32 v68, v69, v188
	v_exp_f32_e32 v203, v68
	s_waitcnt lgkmcnt(3)
	v_mfma_f32_32x32x16_bf16 v[80:95], v[144:147], v[128:131], v[80:95]
	ds_read_b128 v[148:151], v182 offset:12416
	v_sub_f32_e32 v68, v70, v188
	v_exp_f32_e32 v204, v68
	v_sub_f32_e32 v68, v71, v188
	v_exp_f32_e32 v205, v68
	v_cvt_pk_bf16_f32 v68, v198, v199
	v_cvt_pk_bf16_f32 v69, v200, v201
	v_cvt_pk_bf16_f32 v70, v202, v203
	v_cvt_pk_bf16_f32 v71, v204, v205
	s_waitcnt lgkmcnt(3)
	v_mfma_f32_32x32x16_bf16 v[80:95], v[190:193], v[124:127], v[80:95]
	ds_read_b128 v[144:147], v185 offset:12544
	v_sub_f32_e32 v72, v72, v188
	v_exp_f32_e32 v206, v72
	v_sub_f32_e32 v72, v73, v188
	v_exp_f32_e32 v207, v72
	s_waitcnt lgkmcnt(3)
	v_mfma_f32_32x32x16_bf16 v[80:95], v[194:197], v[120:123], v[80:95]
	ds_read_b128 v[152:155], v184 offset:12544
	v_sub_f32_e32 v72, v74, v188
	v_exp_f32_e32 v190, v72
	v_sub_f32_e32 v72, v75, v188
	v_exp_f32_e32 v191, v72
	s_waitcnt lgkmcnt(3)
	v_mfma_f32_32x32x16_bf16 v[80:95], v[64:67], v[116:119], v[80:95]
	ds_read_b128 v[72:75], v183 offset:12544
	v_sub_f32_e32 v76, v76, v188
	v_exp_f32_e32 v192, v76
	v_sub_f32_e32 v76, v77, v188
	v_exp_f32_e32 v193, v76
	v_sub_f32_e32 v76, v78, v188
	v_exp_f32_e32 v194, v76
	v_sub_f32_e32 v76, v79, v188
	s_waitcnt lgkmcnt(3)
	v_mfma_f32_32x32x16_bf16 v[80:95], v[148:151], v[112:115], v[80:95]
	v_exp_f32_e32 v195, v76
	v_pk_add_f32 v[76:77], v[198:199], 0 op_sel_hi:[1,0]
	ds_read_b128 v[64:67], v182 offset:12544
	v_pk_add_f32 v[76:77], v[200:201], v[76:77]
	s_nop 0
	v_pk_add_f32 v[76:77], v[202:203], v[76:77]
	s_nop 0
	v_pk_add_f32 v[76:77], v[204:205], v[76:77]
	s_nop 0
	v_pk_add_f32 v[76:77], v[206:207], v[76:77]
	s_nop 0
	v_pk_add_f32 v[76:77], v[190:191], v[76:77]
	s_nop 0
	v_pk_add_f32 v[76:77], v[192:193], v[76:77]
	s_nop 0
	v_pk_add_f32 v[196:197], v[194:195], v[76:77]
	v_cvt_pk_bf16_f32 v76, v206, v207
	v_cvt_pk_bf16_f32 v77, v190, v191
	v_cvt_pk_bf16_f32 v78, v192, v193
	v_cvt_pk_bf16_f32 v79, v194, v195
	s_waitcnt lgkmcnt(3)
	v_mfma_f32_32x32x16_bf16 v[80:95], v[144:147], v[108:111], v[80:95]
	v_add_u32_e32 v181, v187, v176
	ds_read_b128 v[148:151], v181
	s_waitcnt lgkmcnt(3)
	v_mfma_f32_32x32x16_bf16 v[80:95], v[152:155], v[104:107], v[80:95]
	ds_read_b128 v[144:147], v181 offset:4096
	s_waitcnt lgkmcnt(3)
	v_mfma_f32_32x32x16_bf16 v[80:95], v[72:75], v[100:103], v[80:95]
	ds_read_b128 v[152:155], v181 offset:8192
	s_waitcnt lgkmcnt(3)
	v_mfma_f32_32x32x16_bf16 v[80:95], v[64:67], v[96:99], v[80:95]
	ds_read_b128 v[72:75], v181 offset:12288
	s_waitcnt lgkmcnt(3)
	v_mfma_f32_32x32x16_bf16 v[0:15], v[68:71], v[148:151], v[0:15]
	v_add_u32_e32 v181, v187, v175
	ds_read_b128 v[64:67], v181
	s_waitcnt lgkmcnt(3)
	v_mfma_f32_32x32x16_bf16 v[48:63], v[68:71], v[144:147], v[48:63]
	ds_read_b128 v[148:151], v181 offset:4096
	s_waitcnt lgkmcnt(3)
	v_mfma_f32_32x32x16_bf16 v[32:47], v[68:71], v[152:155], v[32:47]
	ds_read_b128 v[144:147], v181 offset:8192
	s_waitcnt lgkmcnt(3)
	v_mfma_f32_32x32x16_bf16 v[16:31], v[68:71], v[72:75], v[16:31]
	ds_read_b128 v[152:155], v181 offset:12288
	s_waitcnt lgkmcnt(3)
	v_mfma_f32_32x32x16_bf16 v[0:15], v[76:79], v[64:67], v[0:15]
	v_max3_f32 v68, v81, v82, v83
	v_max3_f32 v68, v80, s84, v68
	s_waitcnt lgkmcnt(2)
	v_mfma_f32_32x32x16_bf16 v[48:63], v[76:79], v[148:151], v[48:63]
	v_max3_f32 v64, v85, v86, v87
	v_max3_f32 v64, v68, v84, v64
	s_waitcnt lgkmcnt(1)
	v_mfma_f32_32x32x16_bf16 v[32:47], v[76:79], v[144:147], v[32:47]
	v_max3_f32 v65, v89, v90, v91
	v_max3_f32 v64, v64, v88, v65
	s_waitcnt lgkmcnt(0)
	v_mfma_f32_32x32x16_bf16 v[16:31], v[76:79], v[152:155], v[16:31]
	v_max3_f32 v65, v93, v94, v95
	v_max3_f32 v68, v64, v92, v65
	ds_read_b128 v[64:67], v185
	ds_read_b128 v[152:155], v184
	ds_read_b128 v[148:151], v183
	ds_read_b128 v[144:147], v182
	v_mov_b32_e32 v70, v68
	v_add_f32_e32 v69, v196, v197
	s_nop 0
	v_permlane32_swap_b32_e32 v68, v70
	v_add_f32_e32 v172, v172, v69
	v_max_f32_e32 v69, v70, v70
	v_max_f32_e32 v68, v68, v68
	v_max_f32_e32 v68, v68, v69
	v_cmp_gt_f32_e32 vcc, v68, v189
	s_cbranch_vccz .LBB0_550
	v_max_f32_e32 v68, v68, v68
	v_max_f32_e32 v69, v188, v188
	v_max_f32_e32 v181, v69, v68
	v_sub_f32_e32 v68, v188, v181
	v_exp_f32_e32 v68, v68
	s_and_saveexec_b64 s[6:7], s[4:5]
	ds_write_b32 v167, v68
	s_or_b64 exec, exec, s[6:7]
	v_add_u32_e32 v69, s42, v156
	ds_read_b128 v[70:73], v69 offset:96
	ds_read_b128 v[74:77], v69 offset:64
	ds_read_b128 v[188:191], v69 offset:32
	ds_read_b128 v[192:195], v69
	v_mul_f32_e32 v172, v172, v68
	s_waitcnt lgkmcnt(0)
	v_pk_mul_f32 v[12:13], v[12:13], v[70:71]
	v_pk_mul_f32 v[8:9], v[8:9], v[74:75]
	v_pk_mul_f32 v[4:5], v[4:5], v[188:189]
	v_pk_mul_f32 v[14:15], v[14:15], v[72:73]
	v_pk_mul_f32 v[10:11], v[10:11], v[76:77]
	v_pk_mul_f32 v[6:7], v[6:7], v[190:191]
	v_pk_mul_f32 v[2:3], v[2:3], v[194:195]
	v_pk_mul_f32 v[0:1], v[0:1], v[192:193]
	v_pk_mul_f32 v[60:61], v[60:61], v[70:71]
	v_pk_mul_f32 v[56:57], v[56:57], v[74:75]
	v_pk_mul_f32 v[52:53], v[52:53], v[188:189]
	v_pk_mul_f32 v[62:63], v[62:63], v[72:73]
	v_pk_mul_f32 v[58:59], v[58:59], v[76:77]
	v_pk_mul_f32 v[54:55], v[54:55], v[190:191]
	v_pk_mul_f32 v[50:51], v[50:51], v[194:195]
	v_pk_mul_f32 v[48:49], v[48:49], v[192:193]
	v_pk_mul_f32 v[44:45], v[44:45], v[70:71]
	v_pk_mul_f32 v[40:41], v[40:41], v[74:75]
	v_pk_mul_f32 v[36:37], v[36:37], v[188:189]
	v_pk_mul_f32 v[46:47], v[46:47], v[72:73]
	v_pk_mul_f32 v[42:43], v[42:43], v[76:77]
	v_pk_mul_f32 v[38:39], v[38:39], v[190:191]
	v_pk_mul_f32 v[34:35], v[34:35], v[194:195]
	v_pk_mul_f32 v[32:33], v[32:33], v[192:193]
	v_pk_mul_f32 v[28:29], v[28:29], v[70:71]
	v_pk_mul_f32 v[24:25], v[24:25], v[74:75]
	v_pk_mul_f32 v[20:21], v[20:21], v[188:189]
	v_pk_mul_f32 v[30:31], v[30:31], v[72:73]
	v_pk_mul_f32 v[26:27], v[26:27], v[76:77]
	v_pk_mul_f32 v[22:23], v[22:23], v[190:191]
	v_pk_mul_f32 v[18:19], v[18:19], v[194:195]
	v_pk_mul_f32 v[16:17], v[16:17], v[192:193]
	s_branch .LBB0_551

.LBB0_551:
	v_sub_f32_e32 v68, v80, v181
	v_exp_f32_e32 v80, v68
	v_sub_f32_e32 v68, v81, v181
	v_exp_f32_e32 v81, v68
	s_waitcnt lgkmcnt(3)
	v_mfma_f32_32x32x16_bf16 v[64:79], v[64:67], v[140:143], 0
	ds_read_b128 v[188:191], v185 offset:128
	s_waitcnt lgkmcnt(3)
	v_mfma_f32_32x32x16_bf16 v[64:79], v[152:155], v[136:139], v[64:79]
	v_sub_f32_e32 v82, v82, v181
	v_sub_f32_e32 v83, v83, v181
	ds_read_b128 v[192:195], v184 offset:128
	v_exp_f32_e32 v82, v82
	v_exp_f32_e32 v83, v83
	s_waitcnt lgkmcnt(3)
	v_mfma_f32_32x32x16_bf16 v[64:79], v[148:151], v[132:135], v[64:79]
	v_sub_f32_e32 v84, v84, v181
	v_sub_f32_e32 v85, v85, v181
	ds_read_b128 v[152:155], v183 offset:128
	v_exp_f32_e32 v84, v84
	v_exp_f32_e32 v85, v85
	s_waitcnt lgkmcnt(3)
	v_mfma_f32_32x32x16_bf16 v[64:79], v[144:147], v[128:131], v[64:79]
	v_sub_f32_e32 v86, v86, v181
	v_sub_f32_e32 v87, v87, v181
	ds_read_b128 v[148:151], v182 offset:128
	v_exp_f32_e32 v86, v86
	v_exp_f32_e32 v87, v87
	v_cvt_pk_bf16_f32 v196, v80, v81
	v_cvt_pk_bf16_f32 v197, v82, v83
	v_cvt_pk_bf16_f32 v198, v84, v85
	v_cvt_pk_bf16_f32 v199, v86, v87
	s_waitcnt lgkmcnt(3)
	v_mfma_f32_32x32x16_bf16 v[64:79], v[188:191], v[124:127], v[64:79]
	v_sub_f32_e32 v88, v88, v181
	v_sub_f32_e32 v89, v89, v181
	ds_read_b128 v[144:147], v185 offset:256
	v_exp_f32_e32 v88, v88
	v_exp_f32_e32 v89, v89
	s_waitcnt lgkmcnt(3)
	v_mfma_f32_32x32x16_bf16 v[64:79], v[192:195], v[120:123], v[64:79]
	v_sub_f32_e32 v90, v90, v181
	v_sub_f32_e32 v91, v91, v181
	ds_read_b128 v[188:191], v184 offset:256
	v_exp_f32_e32 v90, v90
	v_exp_f32_e32 v91, v91
	s_waitcnt lgkmcnt(3)
	v_mfma_f32_32x32x16_bf16 v[64:79], v[152:155], v[116:119], v[64:79]
	v_sub_f32_e32 v92, v92, v181
	v_sub_f32_e32 v93, v93, v181
	ds_read_b128 v[192:195], v183 offset:256
	v_exp_f32_e32 v92, v92
	v_exp_f32_e32 v93, v93
	s_waitcnt lgkmcnt(3)
	v_mfma_f32_32x32x16_bf16 v[64:79], v[148:151], v[112:115], v[64:79]
	ds_read_b128 v[152:155], v182 offset:256
	v_add_f32_e64 v182, v80, 0
	v_add_f32_e64 v183, v81, 0
	v_sub_f32_e32 v94, v94, v181
	v_add_f32_e64 v148, v82, v182
	v_add_f32_e64 v149, v83, v183
	v_sub_f32_e32 v95, v95, v181
	v_pk_add_f32 v[148:149], v[84:85], v[148:149]
	v_exp_f32_e32 v94, v94
	v_exp_f32_e32 v95, v95
	v_pk_add_f32 v[148:149], v[86:87], v[148:149]
	s_nop 0
	v_pk_add_f32 v[148:149], v[88:89], v[148:149]
	s_nop 0
	v_pk_add_f32 v[148:149], v[90:91], v[148:149]
	s_nop 0
	v_pk_add_f32 v[148:149], v[92:93], v[148:149]
	s_nop 0
	v_pk_add_f32 v[200:201], v[94:95], v[148:149]
	v_cvt_pk_bf16_f32 v148, v88, v89
	v_cvt_pk_bf16_f32 v149, v90, v91
	v_cvt_pk_bf16_f32 v150, v92, v93
	v_cvt_pk_bf16_f32 v151, v94, v95
	s_waitcnt lgkmcnt(3)
	v_mfma_f32_32x32x16_bf16 v[64:79], v[144:147], v[108:111], v[64:79]
	v_add_u32_e32 v202, v187, v169
	ds_read_b128 v[182:185], v202
	s_waitcnt lgkmcnt(3)
	v_mfma_f32_32x32x16_bf16 v[64:79], v[188:191], v[104:107], v[64:79]
	ds_read_b128 v[144:147], v202 offset:4096
	s_waitcnt lgkmcnt(3)
	v_mfma_f32_32x32x16_bf16 v[64:79], v[192:195], v[100:103], v[64:79]
	ds_read_b128 v[188:191], v202 offset:8192
	s_waitcnt lgkmcnt(3)
	v_mfma_f32_32x32x16_bf16 v[64:79], v[152:155], v[96:99], v[64:79]
	ds_read_b128 v[192:195], v202 offset:12288
	s_waitcnt lgkmcnt(3)
	v_mfma_f32_32x32x16_bf16 v[0:15], v[196:199], v[182:185], v[0:15]
	v_add_u32_e32 v187, v187, v168
	ds_read_b128 v[152:155], v187
	s_waitcnt lgkmcnt(3)
	v_mfma_f32_32x32x16_bf16 v[48:63], v[196:199], v[144:147], v[48:63]
	ds_read_b128 v[182:185], v187 offset:4096
	s_waitcnt lgkmcnt(3)
	v_mfma_f32_32x32x16_bf16 v[32:47], v[196:199], v[188:191], v[32:47]
	ds_read_b128 v[144:147], v187 offset:8192
	s_waitcnt lgkmcnt(3)
	v_mfma_f32_32x32x16_bf16 v[16:31], v[196:199], v[192:195], v[16:31]
	ds_read_b128 v[188:191], v187 offset:12288
	s_waitcnt lgkmcnt(3)
	v_mfma_f32_32x32x16_bf16 v[0:15], v[148:151], v[152:155], v[0:15]
	v_max3_f32 v187, v65, v66, v67
	v_max3_f32 v187, v64, s84, v187
	s_waitcnt lgkmcnt(2)
	v_mfma_f32_32x32x16_bf16 v[48:63], v[148:151], v[182:185], v[48:63]
	v_max3_f32 v152, v69, v70, v71
	v_max3_f32 v152, v187, v68, v152
	s_waitcnt lgkmcnt(1)
	v_mfma_f32_32x32x16_bf16 v[32:47], v[148:151], v[144:147], v[32:47]
	v_max3_f32 v153, v73, v74, v75
	v_max3_f32 v152, v152, v72, v153
	s_waitcnt lgkmcnt(0)
	v_mfma_f32_32x32x16_bf16 v[16:31], v[148:151], v[188:191], v[16:31]
	v_max3_f32 v144, v77, v78, v79
	v_max3_f32 v144, v152, v76, v144
	v_add_f32_e32 v145, v200, v201
	v_add_f32_e32 v172, v172, v145
	v_mov_b32_e32 v145, v144
	s_nop 1
	v_permlane32_swap_b32_e32 v144, v145
	s_waitcnt vmcnt(5) lgkmcnt(0)
	s_barrier
	v_max_f32_e32 v145, v145, v145
	v_max_f32_e32 v144, v144, v144
	s_add_i32 s18, s18, -1
	v_max_f32_e32 v187, v144, v145
	s_cmp_gt_u32 s18, 1
	s_cbranch_scc0 .LBB0_553
	s_mov_b32 s49, s44
	s_mov_b32 s44, s46
	s_mov_b32 s46, s16
	s_branch .LBB0_541

.LBB0_607:
	v_lshl_add_u32 v187, s16, 14, v180
	s_waitcnt lgkmcnt(3)
	v_mfma_f32_32x32x16_bf16 v[80:95], v[80:83], v[140:143], 0
	ds_read_b128 v[190:193], v185 offset:12416
	v_sub_f32_e32 v64, v64, v188
	v_exp_f32_e32 v198, v64
	v_sub_f32_e32 v64, v65, v188
	v_exp_f32_e32 v199, v64
	s_waitcnt lgkmcnt(3)
	v_mfma_f32_32x32x16_bf16 v[80:95], v[152:155], v[136:139], v[80:95]
	ds_read_b128 v[194:197], v184 offset:12416
	v_sub_f32_e32 v64, v66, v188
	v_exp_f32_e32 v200, v64
	v_sub_f32_e32 v64, v67, v188
	v_exp_f32_e32 v201, v64
	s_waitcnt lgkmcnt(3)
	v_mfma_f32_32x32x16_bf16 v[80:95], v[148:151], v[132:135], v[80:95]
	ds_read_b128 v[64:67], v183 offset:12416
	v_sub_f32_e32 v68, v68, v188
	v_exp_f32_e32 v202, v68
	v_sub_f32_e32 v68, v69, v188
	v_exp_f32_e32 v203, v68
	s_waitcnt lgkmcnt(3)
	v_mfma_f32_32x32x16_bf16 v[80:95], v[144:147], v[128:131], v[80:95]
	ds_read_b128 v[148:151], v182 offset:12416
	v_sub_f32_e32 v68, v70, v188
	v_exp_f32_e32 v204, v68
	v_sub_f32_e32 v68, v71, v188
	v_exp_f32_e32 v205, v68
	v_cvt_pk_bf16_f32 v68, v198, v199
	v_cvt_pk_bf16_f32 v69, v200, v201
	v_cvt_pk_bf16_f32 v70, v202, v203
	v_cvt_pk_bf16_f32 v71, v204, v205
	s_waitcnt lgkmcnt(3)
	v_mfma_f32_32x32x16_bf16 v[80:95], v[190:193], v[124:127], v[80:95]
	ds_read_b128 v[144:147], v185 offset:12544
	v_sub_f32_e32 v72, v72, v188
	v_exp_f32_e32 v206, v72
	v_sub_f32_e32 v72, v73, v188
	v_exp_f32_e32 v207, v72
	s_waitcnt lgkmcnt(3)
	v_mfma_f32_32x32x16_bf16 v[80:95], v[194:197], v[120:123], v[80:95]
	ds_read_b128 v[152:155], v184 offset:12544
	v_sub_f32_e32 v72, v74, v188
	v_exp_f32_e32 v190, v72
	v_sub_f32_e32 v72, v75, v188
	v_exp_f32_e32 v191, v72
	s_waitcnt lgkmcnt(3)
	v_mfma_f32_32x32x16_bf16 v[80:95], v[64:67], v[116:119], v[80:95]
	ds_read_b128 v[72:75], v183 offset:12544
	v_sub_f32_e32 v76, v76, v188
	v_exp_f32_e32 v192, v76
	v_sub_f32_e32 v76, v77, v188
	v_exp_f32_e32 v193, v76
	v_sub_f32_e32 v76, v78, v188
	v_exp_f32_e32 v194, v76
	v_sub_f32_e32 v76, v79, v188
	s_waitcnt lgkmcnt(3)
	v_mfma_f32_32x32x16_bf16 v[80:95], v[148:151], v[112:115], v[80:95]
	v_exp_f32_e32 v195, v76
	v_pk_add_f32 v[76:77], v[198:199], 0 op_sel_hi:[1,0]
	ds_read_b128 v[64:67], v182 offset:12544
	v_pk_add_f32 v[76:77], v[200:201], v[76:77]
	s_nop 0
	v_pk_add_f32 v[76:77], v[202:203], v[76:77]
	s_nop 0
	v_pk_add_f32 v[76:77], v[204:205], v[76:77]
	s_nop 0
	v_pk_add_f32 v[76:77], v[206:207], v[76:77]
	s_nop 0
	v_pk_add_f32 v[76:77], v[190:191], v[76:77]
	s_nop 0
	v_pk_add_f32 v[76:77], v[192:193], v[76:77]
	s_nop 0
	v_pk_add_f32 v[196:197], v[194:195], v[76:77]
	v_cvt_pk_bf16_f32 v76, v206, v207
	v_cvt_pk_bf16_f32 v77, v190, v191
	v_cvt_pk_bf16_f32 v78, v192, v193
	v_cvt_pk_bf16_f32 v79, v194, v195
	s_waitcnt lgkmcnt(3)
	v_mfma_f32_32x32x16_bf16 v[80:95], v[144:147], v[108:111], v[80:95]
	v_add_u32_e32 v181, v187, v176
	ds_read_b128 v[148:151], v181
	s_waitcnt lgkmcnt(3)
	v_mfma_f32_32x32x16_bf16 v[80:95], v[152:155], v[104:107], v[80:95]
	ds_read_b128 v[144:147], v181 offset:4096
	s_waitcnt lgkmcnt(3)
	v_mfma_f32_32x32x16_bf16 v[80:95], v[72:75], v[100:103], v[80:95]
	ds_read_b128 v[152:155], v181 offset:8192
	s_waitcnt lgkmcnt(3)
	v_mfma_f32_32x32x16_bf16 v[80:95], v[64:67], v[96:99], v[80:95]
	ds_read_b128 v[72:75], v181 offset:12288
	s_waitcnt lgkmcnt(3)
	v_mfma_f32_32x32x16_bf16 v[0:15], v[68:71], v[148:151], v[0:15]
	v_add_u32_e32 v181, v187, v175
	ds_read_b128 v[64:67], v181
	s_waitcnt lgkmcnt(3)
	v_mfma_f32_32x32x16_bf16 v[48:63], v[68:71], v[144:147], v[48:63]
	ds_read_b128 v[148:151], v181 offset:4096
	s_waitcnt lgkmcnt(3)
	v_mfma_f32_32x32x16_bf16 v[32:47], v[68:71], v[152:155], v[32:47]
	ds_read_b128 v[144:147], v181 offset:8192
	s_waitcnt lgkmcnt(3)
	v_mfma_f32_32x32x16_bf16 v[16:31], v[68:71], v[72:75], v[16:31]
	ds_read_b128 v[152:155], v181 offset:12288
	s_waitcnt lgkmcnt(3)
	v_mfma_f32_32x32x16_bf16 v[0:15], v[76:79], v[64:67], v[0:15]
	v_max3_f32 v68, v81, v82, v83
	v_max3_f32 v68, v80, s84, v68
	s_waitcnt lgkmcnt(2)
	v_mfma_f32_32x32x16_bf16 v[48:63], v[76:79], v[148:151], v[48:63]
	v_max3_f32 v64, v85, v86, v87
	v_max3_f32 v64, v68, v84, v64
	s_waitcnt lgkmcnt(1)
	v_mfma_f32_32x32x16_bf16 v[32:47], v[76:79], v[144:147], v[32:47]
	v_max3_f32 v65, v89, v90, v91
	v_max3_f32 v64, v64, v88, v65
	s_waitcnt lgkmcnt(0)
	v_mfma_f32_32x32x16_bf16 v[16:31], v[76:79], v[152:155], v[16:31]
	v_max3_f32 v65, v93, v94, v95
	v_max3_f32 v68, v64, v92, v65
	ds_read_b128 v[64:67], v185
	ds_read_b128 v[152:155], v184
	ds_read_b128 v[148:151], v183
	ds_read_b128 v[144:147], v182
	v_mov_b32_e32 v70, v68
	v_add_f32_e32 v69, v196, v197
	s_nop 0
	v_permlane32_swap_b32_e32 v68, v70
	v_add_f32_e32 v171, v171, v69
	v_max_f32_e32 v69, v70, v70
	v_max_f32_e32 v68, v68, v68
	v_max_f32_e32 v68, v68, v69
	v_cmp_gt_f32_e32 vcc, v68, v189
	s_cbranch_vccz .LBB0_611
	v_max_f32_e32 v68, v68, v68
	v_max_f32_e32 v69, v188, v188
	v_max_f32_e32 v181, v69, v68
	v_sub_f32_e32 v68, v188, v181
	v_exp_f32_e32 v68, v68
	s_and_saveexec_b64 s[6:7], s[4:5]
	ds_write_b32 v167, v68
	s_or_b64 exec, exec, s[6:7]
	v_add_u32_e32 v69, s24, v156
	ds_read_b128 v[70:73], v69 offset:96
	ds_read_b128 v[74:77], v69 offset:64
	ds_read_b128 v[188:191], v69 offset:32
	ds_read_b128 v[192:195], v69
	v_mul_f32_e32 v171, v171, v68
	s_waitcnt lgkmcnt(0)
	v_pk_mul_f32 v[12:13], v[12:13], v[70:71]
	v_pk_mul_f32 v[8:9], v[8:9], v[74:75]
	v_pk_mul_f32 v[4:5], v[4:5], v[188:189]
	v_pk_mul_f32 v[14:15], v[14:15], v[72:73]
	v_pk_mul_f32 v[10:11], v[10:11], v[76:77]
	v_pk_mul_f32 v[6:7], v[6:7], v[190:191]
	v_pk_mul_f32 v[2:3], v[2:3], v[194:195]
	v_pk_mul_f32 v[0:1], v[0:1], v[192:193]
	v_pk_mul_f32 v[60:61], v[60:61], v[70:71]
	v_pk_mul_f32 v[56:57], v[56:57], v[74:75]
	v_pk_mul_f32 v[52:53], v[52:53], v[188:189]
	v_pk_mul_f32 v[62:63], v[62:63], v[72:73]
	v_pk_mul_f32 v[58:59], v[58:59], v[76:77]
	v_pk_mul_f32 v[54:55], v[54:55], v[190:191]
	v_pk_mul_f32 v[50:51], v[50:51], v[194:195]
	v_pk_mul_f32 v[48:49], v[48:49], v[192:193]
	v_pk_mul_f32 v[44:45], v[44:45], v[70:71]
	v_pk_mul_f32 v[40:41], v[40:41], v[74:75]
	v_pk_mul_f32 v[36:37], v[36:37], v[188:189]
	v_pk_mul_f32 v[46:47], v[46:47], v[72:73]
	v_pk_mul_f32 v[42:43], v[42:43], v[76:77]
	v_pk_mul_f32 v[38:39], v[38:39], v[190:191]
	v_pk_mul_f32 v[34:35], v[34:35], v[194:195]
	v_pk_mul_f32 v[32:33], v[32:33], v[192:193]
	v_pk_mul_f32 v[28:29], v[28:29], v[70:71]
	v_pk_mul_f32 v[24:25], v[24:25], v[74:75]
	v_pk_mul_f32 v[20:21], v[20:21], v[188:189]
	v_pk_mul_f32 v[30:31], v[30:31], v[72:73]
	v_pk_mul_f32 v[26:27], v[26:27], v[76:77]
	v_pk_mul_f32 v[22:23], v[22:23], v[190:191]
	v_pk_mul_f32 v[18:19], v[18:19], v[194:195]
	v_pk_mul_f32 v[16:17], v[16:17], v[192:193]
	s_branch .LBB0_612

.LBB0_612:
	v_sub_f32_e32 v68, v80, v181
	v_exp_f32_e32 v80, v68
	v_sub_f32_e32 v68, v81, v181
	v_exp_f32_e32 v81, v68
	s_waitcnt lgkmcnt(3)
	v_mfma_f32_32x32x16_bf16 v[64:79], v[64:67], v[140:143], 0
	ds_read_b128 v[188:191], v185 offset:128
	s_waitcnt lgkmcnt(3)
	v_mfma_f32_32x32x16_bf16 v[64:79], v[152:155], v[136:139], v[64:79]
	v_sub_f32_e32 v82, v82, v181
	v_sub_f32_e32 v83, v83, v181
	ds_read_b128 v[192:195], v184 offset:128
	v_exp_f32_e32 v82, v82
	v_exp_f32_e32 v83, v83
	s_waitcnt lgkmcnt(3)
	v_mfma_f32_32x32x16_bf16 v[64:79], v[148:151], v[132:135], v[64:79]
	v_sub_f32_e32 v84, v84, v181
	v_sub_f32_e32 v85, v85, v181
	ds_read_b128 v[152:155], v183 offset:128
	v_exp_f32_e32 v84, v84
	v_exp_f32_e32 v85, v85
	s_waitcnt lgkmcnt(3)
	v_mfma_f32_32x32x16_bf16 v[64:79], v[144:147], v[128:131], v[64:79]
	v_sub_f32_e32 v86, v86, v181
	v_sub_f32_e32 v87, v87, v181
	ds_read_b128 v[148:151], v182 offset:128
	v_exp_f32_e32 v86, v86
	v_exp_f32_e32 v87, v87
	v_cvt_pk_bf16_f32 v196, v80, v81
	v_cvt_pk_bf16_f32 v197, v82, v83
	v_cvt_pk_bf16_f32 v198, v84, v85
	v_cvt_pk_bf16_f32 v199, v86, v87
	s_waitcnt lgkmcnt(3)
	v_mfma_f32_32x32x16_bf16 v[64:79], v[188:191], v[124:127], v[64:79]
	v_sub_f32_e32 v88, v88, v181
	v_sub_f32_e32 v89, v89, v181
	ds_read_b128 v[144:147], v185 offset:256
	v_exp_f32_e32 v88, v88
	v_exp_f32_e32 v89, v89
	s_waitcnt lgkmcnt(3)
	v_mfma_f32_32x32x16_bf16 v[64:79], v[192:195], v[120:123], v[64:79]
	v_sub_f32_e32 v90, v90, v181
	v_sub_f32_e32 v91, v91, v181
	ds_read_b128 v[188:191], v184 offset:256
	v_exp_f32_e32 v90, v90
	v_exp_f32_e32 v91, v91
	s_waitcnt lgkmcnt(3)
	v_mfma_f32_32x32x16_bf16 v[64:79], v[152:155], v[116:119], v[64:79]
	v_sub_f32_e32 v92, v92, v181
	v_sub_f32_e32 v93, v93, v181
	ds_read_b128 v[192:195], v183 offset:256
	v_exp_f32_e32 v92, v92
	v_exp_f32_e32 v93, v93
	s_waitcnt lgkmcnt(3)
	v_mfma_f32_32x32x16_bf16 v[64:79], v[148:151], v[112:115], v[64:79]
	ds_read_b128 v[152:155], v182 offset:256
	v_add_f32_e64 v182, v80, 0
	v_add_f32_e64 v183, v81, 0
	v_sub_f32_e32 v94, v94, v181
	v_add_f32_e64 v148, v82, v182
	v_add_f32_e64 v149, v83, v183
	v_sub_f32_e32 v95, v95, v181
	v_pk_add_f32 v[148:149], v[84:85], v[148:149]
	v_exp_f32_e32 v94, v94
	v_exp_f32_e32 v95, v95
	v_pk_add_f32 v[148:149], v[86:87], v[148:149]
	s_nop 0
	v_pk_add_f32 v[148:149], v[88:89], v[148:149]
	s_nop 0
	v_pk_add_f32 v[148:149], v[90:91], v[148:149]
	s_nop 0
	v_pk_add_f32 v[148:149], v[92:93], v[148:149]
	s_nop 0
	v_pk_add_f32 v[200:201], v[94:95], v[148:149]
	v_cvt_pk_bf16_f32 v148, v88, v89
	v_cvt_pk_bf16_f32 v149, v90, v91
	v_cvt_pk_bf16_f32 v150, v92, v93
	v_cvt_pk_bf16_f32 v151, v94, v95
	s_waitcnt lgkmcnt(3)
	v_mfma_f32_32x32x16_bf16 v[64:79], v[144:147], v[108:111], v[64:79]
	v_add_u32_e32 v202, v187, v169
	ds_read_b128 v[182:185], v202
	s_waitcnt lgkmcnt(3)
	v_mfma_f32_32x32x16_bf16 v[64:79], v[188:191], v[104:107], v[64:79]
	ds_read_b128 v[144:147], v202 offset:4096
	s_waitcnt lgkmcnt(3)
	v_mfma_f32_32x32x16_bf16 v[64:79], v[192:195], v[100:103], v[64:79]
	ds_read_b128 v[188:191], v202 offset:8192
	s_waitcnt lgkmcnt(3)
	v_mfma_f32_32x32x16_bf16 v[64:79], v[152:155], v[96:99], v[64:79]
	ds_read_b128 v[192:195], v202 offset:12288
	s_waitcnt lgkmcnt(3)
	v_mfma_f32_32x32x16_bf16 v[0:15], v[196:199], v[182:185], v[0:15]
	v_add_u32_e32 v187, v187, v168
	ds_read_b128 v[152:155], v187
	s_waitcnt lgkmcnt(3)
	v_mfma_f32_32x32x16_bf16 v[48:63], v[196:199], v[144:147], v[48:63]
	ds_read_b128 v[182:185], v187 offset:4096
	s_waitcnt lgkmcnt(3)
	v_mfma_f32_32x32x16_bf16 v[32:47], v[196:199], v[188:191], v[32:47]
	ds_read_b128 v[144:147], v187 offset:8192
	s_waitcnt lgkmcnt(3)
	v_mfma_f32_32x32x16_bf16 v[16:31], v[196:199], v[192:195], v[16:31]
	ds_read_b128 v[188:191], v187 offset:12288
	s_waitcnt lgkmcnt(3)
	v_mfma_f32_32x32x16_bf16 v[0:15], v[148:151], v[152:155], v[0:15]
	v_max3_f32 v187, v65, v66, v67
	v_max3_f32 v187, v64, s84, v187
	s_waitcnt lgkmcnt(2)
	v_mfma_f32_32x32x16_bf16 v[48:63], v[148:151], v[182:185], v[48:63]
	v_max3_f32 v152, v69, v70, v71
	v_max3_f32 v152, v187, v68, v152
	s_waitcnt lgkmcnt(1)
	v_mfma_f32_32x32x16_bf16 v[32:47], v[148:151], v[144:147], v[32:47]
	v_max3_f32 v153, v73, v74, v75
	v_max3_f32 v152, v152, v72, v153
	s_waitcnt lgkmcnt(0)
	v_mfma_f32_32x32x16_bf16 v[16:31], v[148:151], v[188:191], v[16:31]
	v_max3_f32 v144, v77, v78, v79
	v_max3_f32 v144, v152, v76, v144
	v_add_f32_e32 v145, v200, v201
	v_add_f32_e32 v171, v171, v145
	v_mov_b32_e32 v145, v144
	s_nop 1
	v_permlane32_swap_b32_e32 v144, v145
	s_waitcnt vmcnt(5) lgkmcnt(0)
	s_barrier
	v_max_f32_e32 v145, v145, v145
	v_max_f32_e32 v144, v144, v144
	s_add_i32 s31, s31, -1
	v_max_f32_e32 v187, v144, v145
	s_cmp_gt_u32 s31, 1
	s_cbranch_scc0 .LBB0_615
	s_mov_b32 s88, s28
	s_mov_b32 s28, s37
	s_mov_b32 s37, s16
	s_branch .LBB0_602

.LBB0_1324:
	s_add_i32 s80, s80, -1
	s_add_i32 s24, s72, s80
	s_waitcnt vmcnt(4) lgkmcnt(0)
	s_barrier
	s_add_i32 s40, s24, 4
	s_sub_i32 s81, s81, 64
	s_cmp_gt_u32 s40, s72
	s_cbranch_scc0 .LBB0_1328
	s_waitcnt vmcnt(0)
	v_mov_b32_e32 v112, v148
	s_mov_b32 s8, s45
	s_mov_b32 s45, s44
	s_mov_b32 s44, s75
	s_branch .LBB0_1304

.LBB0_1358:
	v_lshl_add_u32 v166, s44, 14, v147
	s_waitcnt lgkmcnt(0)
	v_mfma_f32_32x32x16_bf16 v[80:95], v[124:127], v[108:111], v[80:95]
	v_sub_f32_e32 v64, v64, v170
	v_exp_f32_e32 v174, v64
	v_sub_f32_e32 v64, v65, v170
	v_exp_f32_e32 v175, v64
	v_mfma_f32_32x32x16_bf16 v[80:95], v[120:123], v[104:107], v[80:95]
	v_add_u32_e32 v161, v166, v151
	ds_read_b128 v[124:127], v161 offset:24576
	v_sub_f32_e32 v64, v66, v170
	v_exp_f32_e32 v176, v64
	v_sub_f32_e32 v64, v67, v170
	v_exp_f32_e32 v177, v64
	v_mfma_f32_32x32x16_bf16 v[80:95], v[116:119], v[100:103], v[80:95]
	ds_read_b128 v[64:67], v161 offset:28672
	v_sub_f32_e32 v68, v68, v170
	v_exp_f32_e32 v178, v68
	v_sub_f32_e32 v68, v69, v170
	v_exp_f32_e32 v179, v68
	v_mfma_f32_32x32x16_bf16 v[80:95], v[112:115], v[96:99], v[80:95]
	ds_read_b128 v[116:119], v161 offset:32768
	v_sub_f32_e32 v68, v70, v170
	v_exp_f32_e32 v180, v68
	v_sub_f32_e32 v68, v71, v170
	v_exp_f32_e32 v181, v68
	v_cvt_pk_bf16_f32 v68, v174, v175
	v_cvt_pk_bf16_f32 v69, v176, v177
	v_cvt_pk_bf16_f32 v70, v178, v179
	v_cvt_pk_bf16_f32 v71, v180, v181
	s_waitcnt lgkmcnt(2)
	v_mfma_f32_32x32x16_bf16 v[0:15], v[68:71], v[124:127], v[0:15]
	ds_read_b128 v[112:115], v161 offset:36864
	v_sub_f32_e32 v72, v72, v170
	v_exp_f32_e32 v182, v72
	v_sub_f32_e32 v72, v73, v170
	v_exp_f32_e32 v183, v72
	s_waitcnt lgkmcnt(2)
	v_mfma_f32_32x32x16_bf16 v[48:63], v[68:71], v[64:67], v[48:63]
	v_add_u32_e32 v126, v166, v150
	v_sub_f32_e32 v72, v74, v170
	ds_read_b128 v[120:123], v126 offset:24576
	v_exp_f32_e32 v124, v72
	v_sub_f32_e32 v72, v75, v170
	v_exp_f32_e32 v125, v72
	s_waitcnt lgkmcnt(2)
	v_mfma_f32_32x32x16_bf16 v[32:47], v[68:71], v[116:119], v[32:47]
	v_sub_f32_e32 v72, v76, v170
	ds_read_b128 v[64:67], v126 offset:28672
	v_exp_f32_e32 v76, v72
	v_sub_f32_e32 v72, v77, v170
	v_exp_f32_e32 v77, v72
	v_pk_add_f32 v[116:117], v[174:175], 0 op_sel_hi:[1,0]
	s_waitcnt lgkmcnt(2)
	v_mfma_f32_32x32x16_bf16 v[16:31], v[68:71], v[112:115], v[16:31]
	v_add_f32_e64 v68, v176, v116
	v_add_f32_e64 v69, v177, v117
	v_sub_f32_e32 v78, v78, v170
	v_sub_f32_e32 v79, v79, v170
	v_add_f32_e64 v68, v178, v68
	v_add_f32_e64 v69, v179, v69
	ds_read_b128 v[72:75], v126 offset:32768
	v_exp_f32_e32 v78, v78
	v_exp_f32_e32 v79, v79
	v_pk_add_f32 v[68:69], v[180:181], v[68:69]
	s_nop 0
	v_pk_add_f32 v[68:69], v[182:183], v[68:69]
	s_nop 0
	v_pk_add_f32 v[68:69], v[124:125], v[68:69]
	s_nop 0
	v_pk_add_f32 v[68:69], v[76:77], v[68:69]
	s_nop 0
	v_pk_add_f32 v[112:113], v[78:79], v[68:69]
	v_cvt_pk_bf16_f32 v68, v182, v183
	v_cvt_pk_bf16_f32 v69, v124, v125
	v_cvt_pk_bf16_f32 v70, v76, v77
	v_cvt_pk_bf16_f32 v71, v78, v79
	s_nop 0
	s_waitcnt lgkmcnt(2)
	v_mfma_f32_32x32x16_bf16 v[0:15], v[68:71], v[120:123], v[0:15]
	ds_read_b128 v[76:79], v126 offset:36864
	v_max3_f32 v114, v81, v82, v83
	v_max3_f32 v114, v80, s49, v114
	s_waitcnt lgkmcnt(2)
	v_mfma_f32_32x32x16_bf16 v[48:63], v[68:71], v[64:67], v[48:63]
	v_max3_f32 v115, v85, v86, v87
	v_max3_f32 v114, v114, v84, v115
	s_waitcnt lgkmcnt(1)
	v_mfma_f32_32x32x16_bf16 v[32:47], v[68:71], v[72:75], v[32:47]
	v_max3_f32 v64, v89, v90, v91
	v_max3_f32 v64, v114, v88, v64
	s_waitcnt lgkmcnt(0)
	v_mfma_f32_32x32x16_bf16 v[16:31], v[68:71], v[76:79], v[16:31]
	v_max3_f32 v65, v93, v94, v95
	v_max3_f32 v161, v64, v92, v65
	v_add_f32_e32 v174, v112, v113
	ds_read_b128 v[124:127], v167
	ds_read_b128 v[120:123], v168
	ds_read_b128 v[116:119], v169
	ds_read_b128 v[112:115], v171
	ds_read_b128 v[64:67], v172
	ds_read_b128 v[68:71], v172 offset:16
	ds_read_b128 v[72:75], v172 offset:64
	ds_read_b128 v[76:79], v172 offset:80
	v_mov_b32_e32 v175, v161
	s_nop 1
	v_permlane32_swap_b32_e32 v161, v175
	v_max_f32_e32 v167, v175, v175
	v_max_f32_e32 v161, v161, v161
	v_max_f32_e32 v161, v161, v167
	v_add_f32_e32 v158, v158, v174
	v_cmp_gt_f32_e32 vcc, v161, v173
	s_cbranch_vccz .LBB0_1362
	v_max_f32_e32 v161, v161, v161
	v_max_f32_e32 v167, v170, v170
	v_max_f32_e32 v161, v167, v161
	v_sub_f32_e32 v167, v170, v161
	v_exp_f32_e32 v167, v167
	s_and_saveexec_b64 s[10:11], s[6:7]
	ds_write_b32 v144, v167
	s_or_b64 exec, exec, s[10:11]
	v_add_u32_e32 v180, s70, v128
	ds_read_b128 v[168:171], v180 offset:96
	ds_read_b128 v[172:175], v180 offset:64
	ds_read_b128 v[176:179], v180 offset:32
	ds_read_b128 v[180:183], v180
	v_mul_f32_e32 v158, v158, v167
	s_waitcnt lgkmcnt(0)
	v_pk_mul_f32 v[12:13], v[12:13], v[168:169]
	v_pk_mul_f32 v[8:9], v[8:9], v[172:173]
	v_pk_mul_f32 v[4:5], v[4:5], v[176:177]
	v_pk_mul_f32 v[14:15], v[14:15], v[170:171]
	v_pk_mul_f32 v[10:11], v[10:11], v[174:175]
	v_pk_mul_f32 v[6:7], v[6:7], v[178:179]
	v_pk_mul_f32 v[2:3], v[2:3], v[182:183]
	v_pk_mul_f32 v[0:1], v[0:1], v[180:181]
	v_pk_mul_f32 v[60:61], v[60:61], v[168:169]
	v_pk_mul_f32 v[56:57], v[56:57], v[172:173]
	v_pk_mul_f32 v[52:53], v[52:53], v[176:177]
	v_pk_mul_f32 v[62:63], v[62:63], v[170:171]
	v_pk_mul_f32 v[58:59], v[58:59], v[174:175]
	v_pk_mul_f32 v[54:55], v[54:55], v[178:179]
	v_pk_mul_f32 v[50:51], v[50:51], v[182:183]
	v_pk_mul_f32 v[48:49], v[48:49], v[180:181]
	v_pk_mul_f32 v[44:45], v[44:45], v[168:169]
	v_pk_mul_f32 v[40:41], v[40:41], v[172:173]
	v_pk_mul_f32 v[36:37], v[36:37], v[176:177]
	v_pk_mul_f32 v[46:47], v[46:47], v[170:171]
	v_pk_mul_f32 v[42:43], v[42:43], v[174:175]
	v_pk_mul_f32 v[38:39], v[38:39], v[178:179]
	v_pk_mul_f32 v[34:35], v[34:35], v[182:183]
	v_pk_mul_f32 v[32:33], v[32:33], v[180:181]
	v_pk_mul_f32 v[28:29], v[28:29], v[168:169]
	v_pk_mul_f32 v[24:25], v[24:25], v[172:173]
	v_pk_mul_f32 v[20:21], v[20:21], v[176:177]
	v_pk_mul_f32 v[30:31], v[30:31], v[170:171]
	v_pk_mul_f32 v[26:27], v[26:27], v[174:175]
	v_pk_mul_f32 v[22:23], v[22:23], v[178:179]
	v_pk_mul_f32 v[18:19], v[18:19], v[182:183]
	v_pk_mul_f32 v[16:17], v[16:17], v[180:181]
	s_branch .LBB0_1363

.LBB0_1363:
	s_waitcnt lgkmcnt(0)
	v_mfma_f32_32x32x16_bf16 v[64:79], v[124:127], v[108:111], v[64:79]
	v_sub_f32_e32 v80, v80, v161
	v_sub_f32_e32 v81, v81, v161
	v_exp_f32_e32 v80, v80
	v_exp_f32_e32 v81, v81
	v_mfma_f32_32x32x16_bf16 v[64:79], v[120:123], v[104:107], v[64:79]
	v_add_u32_e32 v167, v166, v145
	v_sub_f32_e32 v82, v82, v161
	v_sub_f32_e32 v83, v83, v161
	ds_read_b128 v[124:127], v167 offset:24576
	v_exp_f32_e32 v82, v82
	v_exp_f32_e32 v83, v83
	v_mfma_f32_32x32x16_bf16 v[64:79], v[116:119], v[100:103], v[64:79]
	v_sub_f32_e32 v84, v84, v161
	v_sub_f32_e32 v85, v85, v161
	ds_read_b128 v[120:123], v167 offset:28672
	v_exp_f32_e32 v84, v84
	v_exp_f32_e32 v85, v85
	v_mfma_f32_32x32x16_bf16 v[64:79], v[112:115], v[96:99], v[64:79]
	v_sub_f32_e32 v86, v86, v161
	v_sub_f32_e32 v87, v87, v161
	ds_read_b128 v[116:119], v167 offset:32768
	v_exp_f32_e32 v86, v86
	v_exp_f32_e32 v87, v87
	v_cvt_pk_bf16_f32 v168, v80, v81
	v_cvt_pk_bf16_f32 v169, v82, v83
	v_cvt_pk_bf16_f32 v170, v84, v85
	v_cvt_pk_bf16_f32 v171, v86, v87
	s_waitcnt lgkmcnt(2)
	v_mfma_f32_32x32x16_bf16 v[0:15], v[168:171], v[124:127], v[0:15]
	ds_read_b128 v[112:115], v167 offset:36864
	v_sub_f32_e32 v88, v88, v161
	v_sub_f32_e32 v89, v89, v161
	v_exp_f32_e32 v88, v88
	v_exp_f32_e32 v89, v89
	s_waitcnt lgkmcnt(2)
	v_mfma_f32_32x32x16_bf16 v[48:63], v[168:171], v[120:123], v[48:63]
	v_add_u32_e32 v172, v166, v146
	v_sub_f32_e32 v90, v90, v161
	v_sub_f32_e32 v91, v91, v161
	ds_read_b128 v[124:127], v172 offset:24576
	v_exp_f32_e32 v90, v90
	v_exp_f32_e32 v91, v91
	s_waitcnt lgkmcnt(2)
	v_mfma_f32_32x32x16_bf16 v[32:47], v[168:171], v[116:119], v[32:47]
	v_sub_f32_e32 v92, v92, v161
	v_sub_f32_e32 v93, v93, v161
	ds_read_b128 v[120:123], v172 offset:28672
	v_exp_f32_e32 v92, v92
	v_exp_f32_e32 v93, v93
	s_waitcnt lgkmcnt(2)
	v_mfma_f32_32x32x16_bf16 v[16:31], v[168:171], v[112:115], v[16:31]
	v_sub_f32_e32 v94, v94, v161
	v_sub_f32_e32 v95, v95, v161
	ds_read_b128 v[116:119], v172 offset:32768
	v_exp_f32_e32 v94, v94
	v_exp_f32_e32 v95, v95
	v_cvt_pk_bf16_f32 v166, v88, v89
	v_cvt_pk_bf16_f32 v167, v90, v91
	v_cvt_pk_bf16_f32 v168, v92, v93
	v_cvt_pk_bf16_f32 v169, v94, v95
	s_nop 0
	s_waitcnt lgkmcnt(2)
	v_mfma_f32_32x32x16_bf16 v[0:15], v[166:169], v[124:127], v[0:15]
	ds_read_b128 v[170:173], v172 offset:36864
	v_max3_f32 v112, v65, v66, v67
	v_max3_f32 v112, v64, s49, v112
	s_waitcnt lgkmcnt(2)
	v_mfma_f32_32x32x16_bf16 v[48:63], v[166:169], v[120:123], v[48:63]
	v_max3_f32 v113, v69, v70, v71
	v_max3_f32 v112, v112, v68, v113
	s_waitcnt lgkmcnt(1)
	v_mfma_f32_32x32x16_bf16 v[32:47], v[166:169], v[116:119], v[32:47]
	v_max3_f32 v113, v73, v74, v75
	v_max3_f32 v112, v112, v72, v113
	s_waitcnt lgkmcnt(0)
	v_mfma_f32_32x32x16_bf16 v[16:31], v[166:169], v[170:173], v[16:31]
	v_max3_f32 v113, v77, v78, v79
	v_max3_f32 v112, v112, v76, v113
	v_mov_b32_e32 v113, v112
	s_and_b64 vcc, exec, s[8:9]
	s_nop 0
	v_permlane32_swap_b32_e32 v112, v113
	s_cbranch_vccnz .LBB0_1365
	s_waitcnt vmcnt(0)
	v_sub_u32_e32 v114, v164, v131
	v_cvt_f32_i32_e32 v114, v114
	v_lshl_add_u32 v115, s75, 8, v160
	v_mul_f32_e32 v114, v139, v114
	ds_write_b32 v115, v114

.LBB0_1366:
	s_waitcnt vmcnt(0)
	v_mov_b32_e32 v164, v148
	s_mov_b32 s44, s75
	s_mov_b32 s75, s45
	s_mov_b32 s45, s83
	s_branch .LBB0_1351

.LBB0_1372:
	s_add_i32 s40, s84, -2
	s_min_i32 s24, s40, 0x100
	s_lshl_b64 s[12:13], s[24:25], 13
	s_lshl_b32 s24, s83, 13
	s_add_i32 m0, s74, s24
	s_min_i32 s24, s40, 0xff
	s_lshl_b64 s[40:41], s[24:25], 14
	s_cmp_eq_u32 s84, 1
	s_cselect_b32 s13, 0, s13
	s_cselect_b32 s12, 0, s12
	v_lshl_add_u64 v[80:81], v[134:135], 0, s[12:13]
	s_cselect_b32 s13, 0, s41
	s_cselect_b32 s12, 0, s40
	global_load_lds_dwordx4 v[80:81], off
	v_lshl_add_u64 v[80:81], v[132:133], 0, s[12:13]
	s_lshl_b32 s12, s83, 14
	s_add_i32 s12, s74, s12
	s_add_i32 m0, s12, 0x6000
	v_lshl_add_u32 v126, s81, 13, v153
	global_load_lds_dwordx4 v[80:81], off
	v_lshl_add_u64 v[80:81], v[80:81], 0, s[26:27]
	s_add_i32 m0, s12, 0x8000
	s_lshl_b32 s12, s81, 8
	global_load_lds_dwordx4 v[80:81], off
	v_add_u32_e32 v115, v126, v152
	v_add_u32_e32 v114, s12, v154
	ds_read_b128 v[208:211], v115 offset:4096
	ds_read_b128 v[80:83], v114 offset:128
	ds_read_b128 v[84:87], v114 offset:144
	ds_read_b128 v[88:91], v114 offset:192
	ds_read_b128 v[92:95], v114 offset:208
	ds_read_b128 v[224:227], v115
	ds_read_b128 v[192:195], v114
	ds_read_b128 v[196:199], v114 offset:16
	ds_read_b128 v[200:203], v114 offset:64
	ds_read_b128 v[204:207], v114 offset:80
	v_med3_i32 v118, v113, 0, v137
	v_lshlrev_b32_e32 v119, 2, v118
	global_load_dword v164, v119, s[54:55]
	v_add_u32_e32 v116, v126, v155
	v_add_u32_e32 v117, v126, v156
	v_add_u32_e32 v118, v126, v157
	s_waitcnt lgkmcnt(5)
	v_mfma_f32_32x32x16_bf16 v[80:95], v[208:211], v[108:111], v[80:95]
	ds_read_b128 v[212:215], v116 offset:4096
	ds_read_b128 v[228:231], v116
	s_waitcnt lgkmcnt(2)
	v_mfma_f32_32x32x16_bf16 v[192:207], v[224:227], v[108:111], v[192:207]
	ds_read_b128 v[216:219], v117 offset:4096
	ds_read_b128 v[232:235], v117
	s_waitcnt lgkmcnt(3)
	v_mfma_f32_32x32x16_bf16 v[80:95], v[212:215], v[104:107], v[80:95]
	s_waitcnt lgkmcnt(2)
	v_mfma_f32_32x32x16_bf16 v[192:207], v[228:231], v[104:107], v[192:207]
	ds_read_b128 v[220:223], v118 offset:4096
	ds_read_b128 v[236:239], v118
	s_waitcnt lgkmcnt(3)
	v_mfma_f32_32x32x16_bf16 v[80:95], v[216:219], v[100:103], v[80:95]
	s_waitcnt lgkmcnt(2)
	v_mfma_f32_32x32x16_bf16 v[192:207], v[232:235], v[100:103], v[192:207]
	s_waitcnt lgkmcnt(1)
	v_mfma_f32_32x32x16_bf16 v[80:95], v[220:223], v[96:99], v[80:95]
	s_waitcnt lgkmcnt(0)
	v_mfma_f32_32x32x16_bf16 v[192:207], v[236:239], v[96:99], v[192:207]
	s_nop 9
	v_max_f32_e32 v119, v81, v81
	v_max_f32_e32 v120, v80, v80
	v_max_f32_e32 v119, v120, v119
	v_max3_f32 v119, v119, v82, v83
	v_max_f32_e32 v240, v193, v193
	v_max_f32_e32 v241, v192, v192
	v_max3_f32 v119, v119, v84, v85
	v_max_f32_e32 v240, v241, v240
	v_max3_f32 v119, v119, v86, v87
	v_max3_f32 v240, v240, v194, v195
	v_max3_f32 v119, v119, v88, v89
	v_max3_f32 v240, v240, v196, v197
	v_max3_f32 v119, v119, v90, v91
	v_max3_f32 v240, v240, v198, v199
	v_max3_f32 v119, v119, v92, v93
	v_max3_f32 v240, v240, v200, v201
	v_max3_f32 v119, v119, v94, v95
	v_max3_f32 v240, v240, v202, v203
	v_mov_b32_e32 v120, v119
	v_max3_f32 v240, v240, v204, v205
	v_max3_f32 v240, v240, v206, v207
	v_permlane32_swap_b32_e32 v119, v120
	v_mov_b32_e32 v241, v240
	v_max_f32_e32 v120, v120, v120
	v_max_f32_e32 v119, v119, v119
	v_permlane32_swap_b32_e32 v240, v241
	v_max_f32_e32 v119, v119, v120
	v_max_f32_e32 v241, v241, v241
	v_max_f32_e32 v240, v240, v240
	v_cmp_lt_f32_e32 vcc, v119, v112
	s_cmp_eq_u64 vcc, exec
	s_cbranch_scc0 .LBB0_1377
	v_max_f32_e32 v166, v240, v241
	v_mov_b64_e32 v[64:65], v[192:193]
	v_mov_b64_e32 v[66:67], v[194:195]
	v_mov_b64_e32 v[68:69], v[196:197]
	v_mov_b64_e32 v[70:71], v[198:199]
	v_mov_b64_e32 v[72:73], v[200:201]
	v_mov_b64_e32 v[74:75], v[202:203]
	v_mov_b64_e32 v[76:77], v[204:205]
	v_mov_b64_e32 v[78:79], v[206:207]
	s_and_b64 vcc, exec, s[8:9]
	s_cbranch_vccnz .LBB0_1375
	v_sub_u32_e32 v242, v148, v131
	v_cvt_f32_i32_e32 v242, v242
	v_lshl_add_u32 v243, s80, 8, v160
	v_mul_f32_e32 v242, v139, v242
	ds_write_b32 v243, v242
.LBB0_1375:
	s_add_i32 s24, s84, -1
	s_mov_b32 s12, s80
	s_cmp_lt_i32 s84, 2
	s_waitcnt vmcnt(4) lgkmcnt(0)
	s_barrier
	v_subrev_u32_e32 v113, 64, v113
	s_mov_b64 s[42:43], 0
	s_mov_b64 s[40:41], s[10:11]
	s_waitcnt vmcnt(0)
	v_mov_b32_e32 v148, v164
	s_mov_b32 s80, s83
	s_mov_b32 s83, s81
	s_mov_b32 s84, 0
	s_cselect_b64 s[44:45], -1, 0
	s_mov_b32 s81, s12
	s_and_b64 vcc, exec, s[44:45]
	s_cbranch_vccz .LBB0_1378
	s_branch .LBB0_1330

.LBB0_1432:
	s_add_i32 s70, s70, -1
	s_waitcnt vmcnt(4) lgkmcnt(0)
	s_barrier
	s_add_i32 s24, s44, s70
	s_add_i32 s30, s24, 4
	s_sub_i32 s50, s50, 64
	s_add_i32 s31, s52, -1
	s_cmp_gt_u32 s30, s44
	v_subrev_u32_e32 v112, 64, v160
	s_cbranch_scc0 .LBB0_1436
	v_mov_b32_e32 v160, v112
	s_mov_b32 s52, s31
	s_waitcnt vmcnt(0)
	v_mov_b32_e32 v112, v148
	s_mov_b32 s8, s43
	s_mov_b32 s43, s38
	s_mov_b32 s38, s36
	s_branch .LBB0_1412

.LBB0_1443:
	v_lshl_add_u32 v163, s24, 14, v147
	s_waitcnt lgkmcnt(0)
	v_mfma_f32_32x32x16_bf16 v[80:95], v[124:127], v[108:111], v[80:95]
	v_sub_f32_e32 v64, v64, v167
	v_exp_f32_e32 v172, v64
	v_sub_f32_e32 v64, v65, v167
	v_exp_f32_e32 v173, v64
	v_mfma_f32_32x32x16_bf16 v[80:95], v[120:123], v[104:107], v[80:95]
	v_add_u32_e32 v161, v163, v152
	ds_read_b128 v[124:127], v161 offset:24576
	v_sub_f32_e32 v64, v66, v167
	v_exp_f32_e32 v174, v64
	v_sub_f32_e32 v64, v67, v167
	v_exp_f32_e32 v175, v64
	v_mfma_f32_32x32x16_bf16 v[80:95], v[116:119], v[100:103], v[80:95]
	ds_read_b128 v[64:67], v161 offset:28672
	v_sub_f32_e32 v68, v68, v167
	v_exp_f32_e32 v176, v68
	v_sub_f32_e32 v68, v69, v167
	v_exp_f32_e32 v177, v68
	v_mfma_f32_32x32x16_bf16 v[80:95], v[112:115], v[96:99], v[80:95]
	ds_read_b128 v[116:119], v161 offset:32768
	v_sub_f32_e32 v68, v70, v167
	v_exp_f32_e32 v178, v68
	v_sub_f32_e32 v68, v71, v167
	v_exp_f32_e32 v179, v68
	v_cvt_pk_bf16_f32 v68, v172, v173
	v_cvt_pk_bf16_f32 v69, v174, v175
	v_cvt_pk_bf16_f32 v70, v176, v177
	v_cvt_pk_bf16_f32 v71, v178, v179
	s_waitcnt lgkmcnt(2)
	v_mfma_f32_32x32x16_bf16 v[0:15], v[68:71], v[124:127], v[0:15]
	ds_read_b128 v[112:115], v161 offset:36864
	v_sub_f32_e32 v72, v72, v167
	v_exp_f32_e32 v180, v72
	v_sub_f32_e32 v72, v73, v167
	v_exp_f32_e32 v181, v72
	s_waitcnt lgkmcnt(2)
	v_mfma_f32_32x32x16_bf16 v[48:63], v[68:71], v[64:67], v[48:63]
	v_add_u32_e32 v126, v163, v151
	v_sub_f32_e32 v72, v74, v167
	ds_read_b128 v[120:123], v126 offset:24576
	v_exp_f32_e32 v124, v72
	v_sub_f32_e32 v72, v75, v167
	v_exp_f32_e32 v125, v72
	s_waitcnt lgkmcnt(2)
	v_mfma_f32_32x32x16_bf16 v[32:47], v[68:71], v[116:119], v[32:47]
	v_sub_f32_e32 v72, v76, v167
	ds_read_b128 v[64:67], v126 offset:28672
	v_exp_f32_e32 v76, v72
	v_sub_f32_e32 v72, v77, v167
	v_exp_f32_e32 v77, v72
	v_pk_add_f32 v[116:117], v[172:173], 0 op_sel_hi:[1,0]
	s_waitcnt lgkmcnt(2)
	v_mfma_f32_32x32x16_bf16 v[16:31], v[68:71], v[112:115], v[16:31]
	v_add_f32_e64 v68, v174, v116
	v_add_f32_e64 v69, v175, v117
	v_sub_f32_e32 v78, v78, v167
	v_sub_f32_e32 v79, v79, v167
	v_add_f32_e64 v68, v176, v68
	v_add_f32_e64 v69, v177, v69
	ds_read_b128 v[72:75], v126 offset:32768
	v_exp_f32_e32 v78, v78
	v_exp_f32_e32 v79, v79
	v_pk_add_f32 v[68:69], v[178:179], v[68:69]
	s_nop 0
	v_pk_add_f32 v[68:69], v[180:181], v[68:69]
	s_nop 0
	v_pk_add_f32 v[68:69], v[124:125], v[68:69]
	s_nop 0
	v_pk_add_f32 v[68:69], v[76:77], v[68:69]
	s_nop 0
	v_pk_add_f32 v[112:113], v[78:79], v[68:69]
	v_cvt_pk_bf16_f32 v68, v180, v181
	v_cvt_pk_bf16_f32 v69, v124, v125
	v_cvt_pk_bf16_f32 v70, v76, v77
	v_cvt_pk_bf16_f32 v71, v78, v79
	s_nop 0
	s_waitcnt lgkmcnt(2)
	v_mfma_f32_32x32x16_bf16 v[0:15], v[68:71], v[120:123], v[0:15]
	ds_read_b128 v[76:79], v126 offset:36864
	v_max3_f32 v114, v81, v82, v83
	v_max3_f32 v114, v80, s49, v114
	s_waitcnt lgkmcnt(2)
	v_mfma_f32_32x32x16_bf16 v[48:63], v[68:71], v[64:67], v[48:63]
	v_max3_f32 v115, v85, v86, v87
	v_max3_f32 v114, v114, v84, v115
	s_waitcnt lgkmcnt(1)
	v_mfma_f32_32x32x16_bf16 v[32:47], v[68:71], v[72:75], v[32:47]
	v_max3_f32 v64, v89, v90, v91
	v_max3_f32 v64, v114, v88, v64
	s_waitcnt lgkmcnt(0)
	v_mfma_f32_32x32x16_bf16 v[16:31], v[68:71], v[76:79], v[16:31]
	v_max3_f32 v65, v93, v94, v95
	v_max3_f32 v161, v64, v92, v65
	v_add_f32_e32 v171, v112, v113
	ds_read_b128 v[124:127], v164
	ds_read_b128 v[120:123], v165
	ds_read_b128 v[116:119], v166
	ds_read_b128 v[112:115], v168
	ds_read_b128 v[64:67], v169
	ds_read_b128 v[68:71], v169 offset:16
	ds_read_b128 v[72:75], v169 offset:64
	ds_read_b128 v[76:79], v169 offset:80
	v_mov_b32_e32 v172, v161
	s_nop 1
	v_permlane32_swap_b32_e32 v161, v172
	v_max_f32_e32 v164, v172, v172
	v_max_f32_e32 v161, v161, v161
	v_max_f32_e32 v161, v161, v164
	v_add_f32_e32 v150, v150, v171
	v_cmp_gt_f32_e32 vcc, v161, v170
	s_cbranch_vccz .LBB0_1447
	v_max_f32_e32 v161, v161, v161
	v_max_f32_e32 v164, v167, v167
	v_max_f32_e32 v161, v164, v161
	v_sub_f32_e32 v164, v167, v161
	v_exp_f32_e32 v164, v164
	s_and_saveexec_b64 s[10:11], s[6:7]
	ds_write_b32 v144, v164
	s_or_b64 exec, exec, s[10:11]
	v_add_u32_e32 v165, s39, v128
	ds_read_b128 v[166:169], v165 offset:96
	ds_read_b128 v[170:173], v165 offset:64
	ds_read_b128 v[174:177], v165 offset:32
	ds_read_b128 v[178:181], v165
	v_mul_f32_e32 v150, v150, v164
	s_waitcnt lgkmcnt(0)
	v_pk_mul_f32 v[12:13], v[12:13], v[166:167]
	v_pk_mul_f32 v[8:9], v[8:9], v[170:171]
	v_pk_mul_f32 v[4:5], v[4:5], v[174:175]
	v_pk_mul_f32 v[14:15], v[14:15], v[168:169]
	v_pk_mul_f32 v[10:11], v[10:11], v[172:173]
	v_pk_mul_f32 v[6:7], v[6:7], v[176:177]
	v_pk_mul_f32 v[2:3], v[2:3], v[180:181]
	v_pk_mul_f32 v[0:1], v[0:1], v[178:179]
	v_pk_mul_f32 v[60:61], v[60:61], v[166:167]
	v_pk_mul_f32 v[56:57], v[56:57], v[170:171]
	v_pk_mul_f32 v[52:53], v[52:53], v[174:175]
	v_pk_mul_f32 v[62:63], v[62:63], v[168:169]
	v_pk_mul_f32 v[58:59], v[58:59], v[172:173]
	v_pk_mul_f32 v[54:55], v[54:55], v[176:177]
	v_pk_mul_f32 v[50:51], v[50:51], v[180:181]
	v_pk_mul_f32 v[48:49], v[48:49], v[178:179]
	v_pk_mul_f32 v[44:45], v[44:45], v[166:167]
	v_pk_mul_f32 v[40:41], v[40:41], v[170:171]
	v_pk_mul_f32 v[36:37], v[36:37], v[174:175]
	v_pk_mul_f32 v[46:47], v[46:47], v[168:169]
	v_pk_mul_f32 v[42:43], v[42:43], v[172:173]
	v_pk_mul_f32 v[38:39], v[38:39], v[176:177]
	v_pk_mul_f32 v[34:35], v[34:35], v[180:181]
	v_pk_mul_f32 v[32:33], v[32:33], v[178:179]
	v_pk_mul_f32 v[28:29], v[28:29], v[166:167]
	v_pk_mul_f32 v[24:25], v[24:25], v[170:171]
	v_pk_mul_f32 v[20:21], v[20:21], v[174:175]
	v_pk_mul_f32 v[30:31], v[30:31], v[168:169]
	v_pk_mul_f32 v[26:27], v[26:27], v[172:173]
	v_pk_mul_f32 v[22:23], v[22:23], v[176:177]
	v_pk_mul_f32 v[18:19], v[18:19], v[180:181]
	v_pk_mul_f32 v[16:17], v[16:17], v[178:179]
	s_branch .LBB0_1448

.LBB0_1448:
	s_waitcnt lgkmcnt(0)
	v_mfma_f32_32x32x16_bf16 v[64:79], v[124:127], v[108:111], v[64:79]
	v_sub_f32_e32 v80, v80, v161
	v_sub_f32_e32 v81, v81, v161
	v_exp_f32_e32 v80, v80
	v_exp_f32_e32 v81, v81
	v_mfma_f32_32x32x16_bf16 v[64:79], v[120:123], v[104:107], v[64:79]
	v_add_u32_e32 v168, v163, v145
	v_sub_f32_e32 v82, v82, v161
	v_sub_f32_e32 v83, v83, v161
	ds_read_b128 v[124:127], v168 offset:24576
	v_exp_f32_e32 v82, v82
	v_exp_f32_e32 v83, v83
	v_mfma_f32_32x32x16_bf16 v[64:79], v[116:119], v[100:103], v[64:79]
	v_sub_f32_e32 v84, v84, v161
	v_sub_f32_e32 v85, v85, v161
	ds_read_b128 v[120:123], v168 offset:28672
	v_exp_f32_e32 v84, v84
	v_exp_f32_e32 v85, v85
	v_mfma_f32_32x32x16_bf16 v[64:79], v[112:115], v[96:99], v[64:79]
	v_sub_f32_e32 v86, v86, v161
	v_sub_f32_e32 v87, v87, v161
	ds_read_b128 v[116:119], v168 offset:32768
	v_exp_f32_e32 v86, v86
	v_exp_f32_e32 v87, v87
	v_cvt_pk_bf16_f32 v164, v80, v81
	v_cvt_pk_bf16_f32 v165, v82, v83
	v_cvt_pk_bf16_f32 v166, v84, v85
	v_cvt_pk_bf16_f32 v167, v86, v87
	s_waitcnt lgkmcnt(2)
	v_mfma_f32_32x32x16_bf16 v[0:15], v[164:167], v[124:127], v[0:15]
	ds_read_b128 v[112:115], v168 offset:36864
	v_sub_f32_e32 v88, v88, v161
	v_sub_f32_e32 v89, v89, v161
	v_exp_f32_e32 v88, v88
	v_exp_f32_e32 v89, v89
	s_waitcnt lgkmcnt(2)
	v_mfma_f32_32x32x16_bf16 v[48:63], v[164:167], v[120:123], v[48:63]
	v_add_u32_e32 v163, v163, v146
	v_sub_f32_e32 v90, v90, v161
	v_sub_f32_e32 v91, v91, v161
	ds_read_b128 v[124:127], v163 offset:24576
	v_exp_f32_e32 v90, v90
	v_exp_f32_e32 v91, v91
	s_waitcnt lgkmcnt(2)
	v_mfma_f32_32x32x16_bf16 v[32:47], v[164:167], v[116:119], v[32:47]
	v_sub_f32_e32 v92, v92, v161
	v_sub_f32_e32 v93, v93, v161
	ds_read_b128 v[120:123], v163 offset:28672
	v_exp_f32_e32 v92, v92
	v_exp_f32_e32 v93, v93
	s_waitcnt lgkmcnt(2)
	v_mfma_f32_32x32x16_bf16 v[16:31], v[164:167], v[112:115], v[16:31]
	v_sub_f32_e32 v94, v94, v161
	v_sub_f32_e32 v95, v95, v161
	ds_read_b128 v[116:119], v163 offset:32768
	v_exp_f32_e32 v94, v94
	v_exp_f32_e32 v95, v95
	v_cvt_pk_bf16_f32 v168, v88, v89
	v_cvt_pk_bf16_f32 v169, v90, v91
	v_cvt_pk_bf16_f32 v170, v92, v93
	v_cvt_pk_bf16_f32 v171, v94, v95
	s_nop 0
	s_waitcnt lgkmcnt(2)
	v_mfma_f32_32x32x16_bf16 v[0:15], v[168:171], v[124:127], v[0:15]
	ds_read_b128 v[164:167], v163 offset:36864
	v_max3_f32 v112, v65, v66, v67
	v_max3_f32 v112, v64, s49, v112
	s_waitcnt lgkmcnt(2)
	v_mfma_f32_32x32x16_bf16 v[48:63], v[168:171], v[120:123], v[48:63]
	v_max3_f32 v113, v69, v70, v71
	v_max3_f32 v112, v112, v68, v113
	s_waitcnt lgkmcnt(1)
	v_mfma_f32_32x32x16_bf16 v[32:47], v[168:171], v[116:119], v[32:47]
	v_max3_f32 v113, v73, v74, v75
	v_max3_f32 v112, v112, v72, v113
	s_waitcnt lgkmcnt(0)
	v_mfma_f32_32x32x16_bf16 v[16:31], v[168:171], v[164:167], v[16:31]
	v_max3_f32 v113, v77, v78, v79
	v_max3_f32 v112, v112, v76, v113
	v_mov_b32_e32 v113, v112
	s_and_b64 vcc, exec, s[8:9]
	s_nop 0
	v_permlane32_swap_b32_e32 v112, v113
	s_cbranch_vccnz .LBB0_1450
	s_waitcnt vmcnt(0)
	v_sub_u32_e32 v114, v148, v131
	v_cvt_f32_i32_e32 v114, v114
	v_lshl_add_u32 v115, s38, 8, v159
	v_mul_f32_e32 v114, v139, v114
	ds_write_b32 v115, v114
.LBB0_1450:
	v_add_f32_e32 v114, 0, v80
	v_add_f32_e32 v115, 0, v81
	v_add_f32_e32 v114, v82, v114
	v_add_f32_e32 v115, v83, v115
	v_add_f32_e32 v114, v84, v114
	v_add_f32_e32 v115, v85, v115
	v_add_f32_e32 v114, v86, v114
	v_add_f32_e32 v115, v87, v115
	v_add_f32_e32 v114, v88, v114
	v_add_f32_e32 v115, v89, v115
	v_add_f32_e32 v114, v90, v114
	v_add_f32_e32 v115, v91, v115
	v_add_f32_e32 v114, v92, v114
	v_add_f32_e32 v115, v93, v115
	v_add_f32_e32 v114, v94, v114
	v_add_f32_e32 v115, v95, v115
	s_waitcnt vmcnt(4) lgkmcnt(0)
	s_barrier
	v_add_f32_e32 v114, v114, v115
	v_max_f32_e32 v112, v112, v112
	v_max_f32_e32 v113, v113, v113
	s_add_i32 s52, s52, -1
	v_add_f32_e32 v150, v150, v114
	v_max_f32_e32 v163, v112, v113
	s_cmp_gt_u32 s52, 1
	v_subrev_u32_e32 v160, 64, v160
	s_cbranch_scc0 .LBB0_1453
	s_waitcnt vmcnt(0)
	v_mov_b32_e32 v148, v162
	s_mov_b32 s43, s38
	s_mov_b32 s38, s36
	s_mov_b32 s36, s24
	s_branch .LBB0_1438
